# relocated prep K/V-cache loops in IN idle tail with write-through sc1 stores
# speedup vs baseline: 1.0832x; 1.0832x over previous
; __device__ __forceinline__ unsigned pk2(float lo, float hi) { f32x2 v = {lo, hi}; bf16v2_t b = __builtin_convertvector(v, bf16v2_t); return __builtin_bit_cast(unsigned, b); }
; __device__ __forceinline__ void prep_phase(const Params& p, char* lds) {
;     ...
;     for (int i = gt; i < 128 * 128 * 16; i += NGT) {
;       const int c8 = i & 15, w = (i >> 4) & 127, b = i >> 11;
;       const float* s = ck + ((size_t)b * 128 + w) * 128 + c8 * 8;
;       const f32x4 a = *(const f32x4*)s, bq = *(const f32x4*)(s + 4);
;       u32x4 o; o.x = pk2(a.x, a.y); o.y = pk2(a.z, a.w); o.z = pk2(bq.x, bq.y); o.w = pk2(bq.z, bq.w);
;       *(u32x4*)(Ks + ((size_t)b * 144 + w) * 128 + c8 * 8) = o;
;     }
;     for (int i = gt; i < 128 * 12 * 16; i += NGT) {
;       const int c8 = i & 15, r = (i >> 4) % 12, b = i / 192;
;       *(u32x4*)(Ks + ((size_t)b * 144 + 132 + r) * 128 + c8 * 8) = u32x4{0u, 0u, 0u, 0u};
;     }
;     for (int i = gt; i < 128 * 16 * 128; i += NGT) {
;       const int kvd = i & 127, w8 = (i >> 7) & 15, b = i >> 11;
;       const float* s = cv + ((size_t)b * 128 + w8 * 8) * 128 + kvd;
;       u32x4 o; o.x = pk2(s[0], s[128]); o.y = pk2(s[256], s[384]); o.z = pk2(s[512], s[640]); o.w = pk2(s[768], s[896]);
;       *(u32x4*)(Vts + ((size_t)b * 128 + kvd) * 144 + w8 * 8) = o;
;     }
;     for (int i = gt; i < 128 * 128 * 3; i += NGT) {
;       const int q = i % 3, r = i / 3;
;       *(u32x2*)(Vts + (size_t)r * 144 + 132 + q * 4) = u32x2{0u, 0u};
.Lkvc_l1:
	v_mov_b32_e32 v21, s101
	v_mad_u32_u24 v21, v21, 0, v20
	v_and_b32_e32 v22, 15, v21
	v_bfe_u32 v23, v21, 4, 7
	v_lshrrev_b32_e32 v19, 11, v21
	v_lshlrev_b32_e32 v18, 5, v22
	v_lshl_add_u32 v18, v23, 9, v18
	v_lshlrev_b32_e32 v17, 4, v22
	v_lshl_add_u32 v17, v23, 8, v17
	v_lshl_add_u32 v22, v19, 16, v18
	v_mad_u32_u24 v23, v19, s10, v17
	v_mov_b32_e32 v25, s101
	v_mad_u32_u24 v25, v25, 1, v20
	v_and_b32_e32 v26, 15, v25
	v_bfe_u32 v27, v25, 4, 7
	v_lshrrev_b32_e32 v19, 11, v25
	v_lshlrev_b32_e32 v18, 5, v26
	v_lshl_add_u32 v18, v27, 9, v18
	v_lshlrev_b32_e32 v17, 4, v26
	v_lshl_add_u32 v17, v27, 8, v17
	v_lshl_add_u32 v26, v19, 16, v18
	v_mad_u32_u24 v27, v19, s10, v17
	v_mov_b32_e32 v29, s101
	v_mad_u32_u24 v29, v29, 2, v20
	v_and_b32_e32 v30, 15, v29
	v_bfe_u32 v31, v29, 4, 7
	v_lshrrev_b32_e32 v19, 11, v29
	v_lshlrev_b32_e32 v18, 5, v30
	v_lshl_add_u32 v18, v31, 9, v18
	v_lshlrev_b32_e32 v17, 4, v30
	v_lshl_add_u32 v17, v31, 8, v17
	v_lshl_add_u32 v30, v19, 16, v18
	v_mad_u32_u24 v31, v19, s10, v17
	v_mov_b32_e32 v33, s101
	v_mad_u32_u24 v33, v33, 3, v20
	v_and_b32_e32 v34, 15, v33
	v_bfe_u32 v35, v33, 4, 7
	v_lshrrev_b32_e32 v19, 11, v33
	v_lshlrev_b32_e32 v18, 5, v34
	v_lshl_add_u32 v18, v35, 9, v18
	v_lshlrev_b32_e32 v17, 4, v34
	v_lshl_add_u32 v17, v35, 8, v17
	v_lshl_add_u32 v34, v19, 16, v18
	v_mad_u32_u24 v35, v19, s10, v17
	v_cmp_gt_u32_e32 vcc, 0x40000, v21
	s_and_saveexec_b64 s[4:5], vcc
	global_load_dwordx4 v[40:43], v22, s[12:13]
	global_load_dwordx4 v[44:47], v22, s[12:13] offset:16
	s_or_b64 exec, exec, s[4:5]
	v_cmp_gt_u32_e32 vcc, 0x40000, v25
	s_and_saveexec_b64 s[4:5], vcc
	global_load_dwordx4 v[48:51], v26, s[12:13]
	global_load_dwordx4 v[52:55], v26, s[12:13] offset:16
	s_or_b64 exec, exec, s[4:5]
	v_cmp_gt_u32_e32 vcc, 0x40000, v29
	s_and_saveexec_b64 s[4:5], vcc
	global_load_dwordx4 v[56:59], v30, s[12:13]
	global_load_dwordx4 v[60:63], v30, s[12:13] offset:16
	s_or_b64 exec, exec, s[4:5]
	v_cmp_gt_u32_e32 vcc, 0x40000, v33
	s_and_saveexec_b64 s[4:5], vcc
	global_load_dwordx4 v[64:67], v34, s[12:13]
	global_load_dwordx4 v[68:71], v34, s[12:13] offset:16
	s_or_b64 exec, exec, s[4:5]
	s_waitcnt vmcnt(0)
	v_cvt_pk_bf16_f32 v40, v40, v41
	v_cvt_pk_bf16_f32 v41, v42, v43
	v_cvt_pk_bf16_f32 v42, v44, v45
	v_cvt_pk_bf16_f32 v43, v46, v47
	v_cvt_pk_bf16_f32 v48, v48, v49
	v_cvt_pk_bf16_f32 v49, v50, v51
	v_cvt_pk_bf16_f32 v50, v52, v53
	v_cvt_pk_bf16_f32 v51, v54, v55
	v_cvt_pk_bf16_f32 v56, v56, v57
	v_cvt_pk_bf16_f32 v57, v58, v59
	v_cvt_pk_bf16_f32 v58, v60, v61
	v_cvt_pk_bf16_f32 v59, v62, v63
	v_cvt_pk_bf16_f32 v64, v64, v65
	v_cvt_pk_bf16_f32 v65, v66, v67
	v_cvt_pk_bf16_f32 v66, v68, v69
	v_cvt_pk_bf16_f32 v67, v70, v71
	v_cmp_gt_u32_e32 vcc, 0x40000, v21
	s_and_saveexec_b64 s[4:5], vcc
	global_store_dwordx4 v23, v[40:43], s[24:25] sc1
	s_or_b64 exec, exec, s[4:5]
	v_cmp_gt_u32_e32 vcc, 0x40000, v25
	s_and_saveexec_b64 s[4:5], vcc
	global_store_dwordx4 v27, v[48:51], s[24:25] sc1
	s_or_b64 exec, exec, s[4:5]
	v_cmp_gt_u32_e32 vcc, 0x40000, v29
	s_and_saveexec_b64 s[4:5], vcc
	global_store_dwordx4 v31, v[56:59], s[24:25] sc1
	s_or_b64 exec, exec, s[4:5]
	v_cmp_gt_u32_e32 vcc, 0x40000, v33
	s_and_saveexec_b64 s[4:5], vcc
	global_store_dwordx4 v35, v[64:67], s[24:25] sc1
	s_or_b64 exec, exec, s[4:5]
	v_mov_b32_e32 v19, s101
	v_mad_u32_u24 v20, v19, 4, v20
	v_cmp_gt_u32_e32 vcc, 0x40000, v20
	s_cbranch_vccnz .Lkvc_l1
	s_mov_b64 s[14:15], s[24:25]
	s_movk_i32 s3, 0x6000
	v_cmp_gt_i32_e32 vcc, s3, v245
	s_and_saveexec_b64 s[4:5], vcc
	s_cbranch_execz .Lkvc_46
	v_readlane_b32 s3, v244, 33
	s_nop 3
	s_sub_u32 s3, s3, s99
	v_mov_b32_e32 v3, 0
	s_mov_b64 s[6:7], 0
	v_lshl_or_b32 v1, s3, 12, v247
	s_lshl_b32 s3, s100, 12
	s_mov_b32 s8, 0x2aaaaaab
	s_movk_i32 s9, 0x90
	v_mov_b32_e32 v6, v3
	v_mov_b32_e32 v7, v3
	v_mov_b32_e32 v8, v3
	v_mov_b32_e32 v9, v3
	s_movk_i32 s10, 0x5fff
	v_mov_b32_e32 v4, v245
.Lkvc_45:
	v_ashrrev_i32_e32 v5, 4, v4
	v_mul_hi_i32 v2, v4, s8
	v_and_b32_e32 v10, 0x78, v1
	v_mul_hi_i32 v11, v5, s8
	v_lshrrev_b32_e32 v12, 31, v2
	v_ashrrev_i32_e32 v13, 5, v2
	v_lshlrev_b32_e32 v2, 1, v10
	v_lshrrev_b32_e32 v10, 31, v11
	v_lshrrev_b32_e32 v11, 1, v11
	v_add_u32_e32 v10, v11, v10
	v_mul_lo_u32 v10, v10, 12
	v_sub_u32_e32 v10, v5, v10
	v_add_u32_e32 v12, v13, v12
	v_ashrrev_i32_e32 v11, 31, v10
	v_mad_i64_i32 v[10:11], s[12:13], v12, s9, v[10:11]
	v_lshlrev_b64 v[10:11], 8, v[10:11]
	v_add_u32_e32 v4, s101, v4
	v_lshl_add_u64 v[10:11], s[14:15], 0, v[10:11]
	v_cmp_lt_i32_e32 vcc, s10, v4
	v_lshl_add_u64 v[10:11], v[10:11], 0, v[2:3]
	s_or_b64 s[6:7], vcc, s[6:7]
	v_add_co_u32_e32 v10, vcc, 0x8000, v10
	v_add_u32_e32 v1, s3, v1
	s_nop 0
	v_addc_co_u32_e32 v11, vcc, 0, v11, vcc
	global_store_dwordx4 v[10:11], v[6:9], off offset:1024 sc1
	s_andn2_b64 exec, exec, s[6:7]
	s_cbranch_execnz .Lkvc_45

; __device__ __forceinline__ void prep_phase(const Params& p, char* lds) {
;     ...
;     for (int i = gt; i < 128 * 124 * 32; i += NGT) {
;       const int c4 = i & 31, w = (i >> 5) % 124, b = i / (124 * 32);
;       const size_t so = ((size_t)b * 128 + w + 4) * 128 + c4 * 4, dof = ((size_t)b * 128 + w) * 128 + c4 * 4;
;       *(f32x4*)(p.out + O_KS + dof) = *(const f32x4*)(ck + so);
;       *(f32x4*)(p.out + O_VS + dof) = *(const f32x4*)(cv + so);
;     }
.Lkvc_l5:
	v_mov_b32_e32 v21, s101
	v_mad_u32_u24 v21, v21, 0, v20
	v_and_b32_e32 v19, 31, v21
	v_lshrrev_b32_e32 v18, 5, v21
	v_mul_hi_u32 v17, v18, v16
	v_mul_u32_u24_e32 v23, 0x7c, v17
	v_sub_u32_e32 v18, v18, v23
	v_lshlrev_b32_e32 v19, 4, v19
	v_lshl_add_u32 v19, v18, 9, v19
	v_lshl_add_u32 v23, v17, 16, v19
	v_add_u32_e32 v22, 0x800, v23
	v_mov_b32_e32 v25, s101
	v_mad_u32_u24 v25, v25, 1, v20
	v_and_b32_e32 v19, 31, v25
	v_lshrrev_b32_e32 v18, 5, v25
	v_mul_hi_u32 v17, v18, v16
	v_mul_u32_u24_e32 v27, 0x7c, v17
	v_sub_u32_e32 v18, v18, v27
	v_lshlrev_b32_e32 v19, 4, v19
	v_lshl_add_u32 v19, v18, 9, v19
	v_lshl_add_u32 v27, v17, 16, v19
	v_add_u32_e32 v26, 0x800, v27
	v_mov_b32_e32 v29, s101
	v_mad_u32_u24 v29, v29, 2, v20
	v_and_b32_e32 v19, 31, v29
	v_lshrrev_b32_e32 v18, 5, v29
	v_mul_hi_u32 v17, v18, v16
	v_mul_u32_u24_e32 v31, 0x7c, v17
	v_sub_u32_e32 v18, v18, v31
	v_lshlrev_b32_e32 v19, 4, v19
	v_lshl_add_u32 v19, v18, 9, v19
	v_lshl_add_u32 v31, v17, 16, v19
	v_add_u32_e32 v30, 0x800, v31
	v_mov_b32_e32 v33, s101
	v_mad_u32_u24 v33, v33, 3, v20
	v_and_b32_e32 v19, 31, v33
	v_lshrrev_b32_e32 v18, 5, v33
	v_mul_hi_u32 v17, v18, v16
	v_mul_u32_u24_e32 v35, 0x7c, v17
	v_sub_u32_e32 v18, v18, v35
	v_lshlrev_b32_e32 v19, 4, v19
	v_lshl_add_u32 v19, v18, 9, v19
	v_lshl_add_u32 v35, v17, 16, v19
	v_add_u32_e32 v34, 0x800, v35
	v_mov_b32_e32 v37, s101
	v_mad_u32_u24 v37, v37, 4, v20
	v_and_b32_e32 v19, 31, v37
	v_lshrrev_b32_e32 v18, 5, v37
	v_mul_hi_u32 v17, v18, v16
	v_mul_u32_u24_e32 v39, 0x7c, v17
	v_sub_u32_e32 v18, v18, v39
	v_lshlrev_b32_e32 v19, 4, v19
	v_lshl_add_u32 v19, v18, 9, v19
	v_lshl_add_u32 v39, v17, 16, v19
	v_add_u32_e32 v38, 0x800, v39
	v_mov_b32_e32 v41, s101
	v_mad_u32_u24 v41, v41, 5, v20
	v_and_b32_e32 v19, 31, v41
	v_lshrrev_b32_e32 v18, 5, v41
	v_mul_hi_u32 v17, v18, v16
	v_mul_u32_u24_e32 v43, 0x7c, v17
	v_sub_u32_e32 v18, v18, v43
	v_lshlrev_b32_e32 v19, 4, v19
	v_lshl_add_u32 v19, v18, 9, v19
	v_lshl_add_u32 v43, v17, 16, v19
	v_add_u32_e32 v42, 0x800, v43
	v_cmp_gt_u32_e32 vcc, 0x7c000, v21
	s_and_saveexec_b64 s[10:11], vcc
	global_load_dwordx4 v[48:51], v22, s[12:13]
	global_load_dwordx4 v[52:55], v22, s[14:15]
	s_or_b64 exec, exec, s[10:11]
	v_cmp_gt_u32_e32 vcc, 0x7c000, v25
	s_and_saveexec_b64 s[10:11], vcc
	global_load_dwordx4 v[56:59], v26, s[12:13]
	global_load_dwordx4 v[60:63], v26, s[14:15]
	s_or_b64 exec, exec, s[10:11]
	v_cmp_gt_u32_e32 vcc, 0x7c000, v29
	s_and_saveexec_b64 s[10:11], vcc
	global_load_dwordx4 v[64:67], v30, s[12:13]
	global_load_dwordx4 v[68:71], v30, s[14:15]
	s_or_b64 exec, exec, s[10:11]
	v_cmp_gt_u32_e32 vcc, 0x7c000, v33
	s_and_saveexec_b64 s[10:11], vcc
	global_load_dwordx4 v[72:75], v34, s[12:13]
	global_load_dwordx4 v[76:79], v34, s[14:15]
	s_or_b64 exec, exec, s[10:11]
	v_cmp_gt_u32_e32 vcc, 0x7c000, v37
	s_and_saveexec_b64 s[10:11], vcc
	global_load_dwordx4 v[80:83], v38, s[12:13]
	global_load_dwordx4 v[84:87], v38, s[14:15]
	s_or_b64 exec, exec, s[10:11]
	v_cmp_gt_u32_e32 vcc, 0x7c000, v41
	s_and_saveexec_b64 s[10:11], vcc
	global_load_dwordx4 v[88:91], v42, s[12:13]
	global_load_dwordx4 v[92:95], v42, s[14:15]
	s_or_b64 exec, exec, s[10:11]
	s_waitcnt vmcnt(0)
	v_cmp_gt_u32_e32 vcc, 0x7c000, v21
	s_and_saveexec_b64 s[10:11], vcc
	global_store_dwordx4 v23, v[48:51], s[4:5] sc1
	global_store_dwordx4 v23, v[52:55], s[6:7] sc1
	s_or_b64 exec, exec, s[10:11]
	v_cmp_gt_u32_e32 vcc, 0x7c000, v25
	s_and_saveexec_b64 s[10:11], vcc
	global_store_dwordx4 v27, v[56:59], s[4:5] sc1
	global_store_dwordx4 v27, v[60:63], s[6:7] sc1
	s_or_b64 exec, exec, s[10:11]
	v_cmp_gt_u32_e32 vcc, 0x7c000, v29
	s_and_saveexec_b64 s[10:11], vcc
	global_store_dwordx4 v31, v[64:67], s[4:5] sc1
	global_store_dwordx4 v31, v[68:71], s[6:7] sc1
	s_or_b64 exec, exec, s[10:11]
	v_cmp_gt_u32_e32 vcc, 0x7c000, v33
	s_and_saveexec_b64 s[10:11], vcc
	global_store_dwordx4 v35, v[72:75], s[4:5] sc1
	global_store_dwordx4 v35, v[76:79], s[6:7] sc1
	s_or_b64 exec, exec, s[10:11]
	v_cmp_gt_u32_e32 vcc, 0x7c000, v37
	s_and_saveexec_b64 s[10:11], vcc
	global_store_dwordx4 v39, v[80:83], s[4:5] sc1
	global_store_dwordx4 v39, v[84:87], s[6:7] sc1
	s_or_b64 exec, exec, s[10:11]
	v_cmp_gt_u32_e32 vcc, 0x7c000, v41
	s_and_saveexec_b64 s[10:11], vcc
	global_store_dwordx4 v43, v[88:91], s[4:5] sc1
	global_store_dwordx4 v43, v[92:95], s[6:7] sc1
	s_or_b64 exec, exec, s[10:11]
	v_mov_b32_e32 v19, s101
	v_mad_u32_u24 v20, v19, 6, v20
	v_cmp_gt_u32_e32 vcc, 0x7c000, v20
	s_cbranch_vccnz .Lkvc_l5
	v_readlane_b32 s0, v246, 0
	v_readlane_b32 s1, v246, 1
	v_readlane_b32 s2, v246, 2
	v_readlane_b32 s3, v246, 3
	v_readlane_b32 s4, v246, 4
	v_readlane_b32 s5, v246, 5
	v_readlane_b32 s6, v246, 6
	v_readlane_b32 s7, v246, 7
	v_readlane_b32 s8, v246, 8
	v_readlane_b32 s9, v246, 9
	v_readlane_b32 s10, v246, 10
	v_readlane_b32 s11, v246, 11
	v_readlane_b32 s12, v246, 12
	v_readlane_b32 s13, v246, 13
	v_readlane_b32 s14, v246, 14
	v_readlane_b32 s15, v246, 15
	v_readlane_b32 s16, v246, 16
	v_readlane_b32 s17, v246, 17
	v_readlane_b32 s18, v246, 18
	v_readlane_b32 s19, v246, 19
	v_readlane_b32 s20, v246, 20
	v_readlane_b32 s21, v246, 21
	v_readlane_b32 s22, v246, 22
	v_readlane_b32 s23, v246, 23
	v_readlane_b32 s24, v246, 24
	v_readlane_b32 s25, v246, 25
	v_lshlrev_b32_e32 v1, 2, v0
	s_waitcnt vmcnt(0)
	s_barrier
